# v92 + P13 phase code moved by 16 bytes (240-byte compensation at the next phase entry); repeat-amplified scan showed P13 7 percent faster at this placement
# speedup vs baseline: 1.0045x; 1.0045x over previous
.LBB0_3464:
	s_nop 0
	s_nop 0
	s_nop 0
	s_nop 0
	s_cmp_lt_i32 s84, 14
	s_cselect_b64 s[0:1], -1, 0
	s_cmp_gt_i32 s85, 13
	s_cselect_b64 s[2:3], -1, 0
	s_and_b64 s[0:1], s[0:1], s[2:3]
	s_andn2_b64 vcc, exec, s[0:1]
	s_cbranch_vccnz .LBB0_3697
	s_cmpk_lt_i32 s86, 0x200
	s_cselect_b64 s[0:1], -1, 0
	s_cmpk_gt_i32 s86, 0x1ff
	v_readfirstlane_b32 s33, v170
	s_waitcnt lgkmcnt(0)
	s_barrier
	s_cbranch_scc1 .LBB0_3467
	s_ashr_i32 s2, s86, 31
	s_lshr_b32 s2, s2, 29
	s_add_i32 s2, s86, s2
	s_ashr_i32 s3, s2, 3
	s_and_b32 s2, s2, -8
	s_sub_i32 s2, s86, s2
	s_lshl_b32 s5, s2, 6
	s_mul_i32 s4, s2, 0x41
	s_cmp_lt_i32 s2, 0
	s_cselect_b32 s2, s4, s5
	s_add_i32 s2, s2, s3
	s_ashr_i32 s3, s2, 31
	s_lshr_b32 s3, s3, 27
	s_add_i32 s3, s2, s3
	s_ashr_i32 s4, s3, 5
	s_and_b32 s3, s3, 0xffe0
	s_sub_i32 s2, s2, s3
	s_bfe_i32 s3, s2, 0x80000
	s_bfe_u32 s3, s3, 0x3000c
	s_add_i32 s3, s2, s3
	s_bfe_i32 s5, s3, 0x80000
	s_and_b32 s3, s3, 0xf8
	s_sub_i32 s2, s2, s3
	s_lshl_b32 s4, s4, 3
	s_sext_i32_i16 s5, s5
	s_sext_i32_i8 s2, s2
	s_add_i32 s57, s4, s2
	s_ashr_i32 s8, s5, 3

.LBB0_3697:
	s_nop 0
	s_nop 0
	s_nop 0
	s_nop 0
	s_nop 0
	s_nop 0
	s_nop 0
	s_nop 0
	s_nop 0
	s_nop 0
	s_nop 0
	s_nop 0
	s_nop 0
	s_nop 0
	s_nop 0
	s_nop 0
	s_nop 0
	s_nop 0
	s_nop 0
	s_nop 0
	s_nop 0
	s_nop 0
	s_nop 0
	s_nop 0
	s_nop 0
	s_nop 0
	s_nop 0
	s_nop 0
	s_nop 0
	s_nop 0
	s_nop 0
	s_nop 0
	s_nop 0
	s_nop 0
	s_nop 0
	s_nop 0
	s_nop 0
	s_nop 0
	s_nop 0
	s_nop 0
	s_nop 0
	s_nop 0
	s_nop 0
	s_nop 0
	s_nop 0
	s_nop 0
	s_nop 0
	s_nop 0
	s_nop 0
	s_nop 0
	s_nop 0
	s_nop 0
	s_nop 0
	s_nop 0
	s_nop 0
	s_nop 0
	s_nop 0
	s_nop 0
	s_nop 0
	s_nop 0
	s_cmp_lt_i32 s84, 15
	s_cselect_b64 s[0:1], -1, 0
	s_cmp_gt_i32 s85, 14
	s_cselect_b64 s[2:3], -1, 0
	s_and_b64 s[0:1], s[0:1], s[2:3]
	s_andn2_b64 vcc, exec, s[0:1]
	s_cbranch_vccnz .LBB0_3772
	s_cmpk_gt_i32 s78, 0x1fff
	s_cbranch_scc1 .LBB0_3701
	s_waitcnt vmcnt(11)
	v_lshlrev_b32_e32 v18, 5, v230
	global_load_dwordx4 v[2:5], v18, s[26:27] offset:2048
	global_load_dwordx4 v[6:9], v18, s[26:27] offset:2064
	global_load_dwordx4 v[10:13], v18, s[26:27]
	global_load_dwordx4 v[14:17], v18, s[26:27] offset:16
	s_lshl_b32 s2, s78, 2
	s_ashr_i32 s3, s2, 31
	s_lshl_b32 s0, s22, 5
	s_lshl_b64 s[4:5], s[2:3], 12
	s_add_u32 s4, s28, s4
	v_mov_b32_e32 v19, 0
	s_addc_u32 s5, s29, s5
	v_lshl_add_u64 v[20:21], s[4:5], 0, v[18:19]
	s_mov_b64 s[4:5], 0x3810
	s_ashr_i32 s1, s0, 31
	s_lshl_b64 s[6:7], s[2:3], 11
	v_lshl_add_u64 v[20:21], v[20:21], 0, s[4:5]
	s_lshl_b64 s[4:5], s[0:1], 12
	s_waitcnt vmcnt(14)
	v_lshl_or_b32 v22, v230, 4, s6
	v_mov_b32_e32 v23, s7
	s_lshl_b64 s[6:7], s[0:1], 11
	s_lshl_b64 s[8:9], s[2:3], 6
	s_lshl_b64 s[10:11], s[0:1], 6
	s_waitcnt lgkmcnt(0)
	v_mov_b32_e32 v1, 0x5d00000
	v_mov_b32_e32 v18, 0x358637bd
	s_mov_b32 s1, 0x1b00000
	s_mov_b32 s3, 0x1b01000
	s_movk_i32 s14, 0xd000
	s_movk_i32 s15, 0xe000
	s_movk_i32 s16, 0xf000
